# all 7 residual-GEMM epilogues rewritten (batched residual loads, counted waits)
# baseline (speedup 1.0000x reference)
; #define EPI_LOOP_ROWS _Pragma("unroll") for (int ai = 0; ai < 2; ++ai) _Pragma("unroll") for (int m = 0; m < 4; ++m)
; #define EPI_LOOP_BJ _Pragma("unroll") for (int bj = 0; bj < 2; ++bj)
;     DI void operator()(const AccT& acc, int brow, int bcol, int wr, int wc, int fr, int fq) const {
;         EPI_LOOP_BJ { const int col = bcol + bj * 128 + wc * 32 + fq * 8;
;             const f32x4 g0 = *(const f32x4*)(gate + col), g1 = *(const f32x4*)(gate + col + 4); f32x4 b0 = (f32x4){0.f, 0.f, 0.f, 0.f}, b1 = b0; if (bias) { b0 = *(const f32x4*)(bias + col); b1 = *(const f32x4*)(bias + col + 4); }
;             EPI_LOOP_ROWS { const size_t eo = (size_t)(ai * 128 + wr * 64 + m * 16 + fr) * D + col; float* q = base + eo;
;                 f32x4 x0 = (f32x4){0.f, 0.f, 0.f, 0.f}, x1 = x0; if (rmw) { x0 = *(const f32x4*)(src + eo); x1 = *(const f32x4*)(src + eo + 4); }
.LBB0_857:
	v_lshrrev_b32_e32 v128, 1, v136
	v_and_b32_e32 v129, 0x60, v128
	v_and_b32_e32 v128, 24, v128
	v_add3_u32 v158, v129, s57, v128
	v_ashrrev_i32_e32 v159, 31, v158
	v_lshlrev_b64 v[138:139], 2, v[158:159]
	v_lshl_add_u64 v[160:161], s[4:5], 0, v[138:139]
	global_load_dwordx4 v[128:131], v[160:161], off offset:16
	global_load_dwordx4 v[132:135], v[160:161], off
	v_and_b32_e32 v137, 15, v136
	v_ashrrev_i32_e32 v136, 2, v136
	s_movk_i32 s4, 0xffc0
	v_and_or_b32 v164, v136, s4, v137
	v_ashrrev_i32_e32 v165, 31, v164
	v_lshlrev_b64 v[136:137], 12, v[164:165]
	v_lshl_add_u64 v[162:163], s[38:39], 0, v[136:137]
	v_cndmask_b32_e64 v137, 0, 1, s[14:15]
	v_lshl_add_u64 v[166:167], v[162:163], 0, v[138:139]
	v_mov_b32_e32 v136, 0
	v_cmp_ne_u32_e64 s[4:5], 1, v137
	global_load_dwordx4 v[172:175], v[160:161], off offset:528
	global_load_dwordx4 v[136:139], v[160:161], off offset:512
	v_mov_b32_e32 v142, v166
	v_mov_b32_e32 v143, v167
	v_add_co_u32_e32 v144, vcc, 0x10000, v166
	s_nop 1
	v_addc_co_u32_e32 v145, vcc, 0, v167, vcc
	v_add_co_u32_e32 v158, vcc, 0x20000, v166
	s_nop 1
	v_addc_co_u32_e32 v159, vcc, 0, v167, vcc
	v_add_co_u32_e32 v162, vcc, 0x30000, v166
	s_nop 1
	v_addc_co_u32_e32 v163, vcc, 0, v167, vcc
	s_and_b64 vcc, exec, s[14:15]
	s_cbranch_vccz .Lrep_0_0_nold
	global_load_dwordx4 v[176:179], v[142:143], off
	global_load_dwordx4 v[180:183], v[142:143], off offset:16
	global_load_dwordx4 v[184:187], v[144:145], off
	global_load_dwordx4 v[188:191], v[144:145], off offset:16
	global_load_dwordx4 v[192:195], v[158:159], off
	global_load_dwordx4 v[196:199], v[158:159], off offset:16
	global_load_dwordx4 v[200:203], v[162:163], off
	global_load_dwordx4 v[204:207], v[162:163], off offset:16
	s_branch .Lrep_0_0_go

; #define EPI_LOOP_ROWS _Pragma("unroll") for (int ai = 0; ai < 2; ++ai) _Pragma("unroll") for (int m = 0; m < 4; ++m)
; #define EPI_LOOP_BJ _Pragma("unroll") for (int bj = 0; bj < 2; ++bj)
;     DI void operator()(const AccT& acc, int brow, int bcol, int wr, int wc, int fr, int fq) const {
;         EPI_LOOP_BJ { const int col = bcol + bj * 128 + wc * 32 + fq * 8;
;             const f32x4 g0 = *(const f32x4*)(gate + col), g1 = *(const f32x4*)(gate + col + 4); f32x4 b0 = (f32x4){0.f, 0.f, 0.f, 0.f}, b1 = b0; if (bias) { b0 = *(const f32x4*)(bias + col); b1 = *(const f32x4*)(bias + col + 4); }
;             EPI_LOOP_ROWS { const size_t eo = (size_t)(ai * 128 + wr * 64 + m * 16 + fr) * D + col; float* q = base + eo;
;                 f32x4 x0 = (f32x4){0.f, 0.f, 0.f, 0.f}, x1 = x0; if (rmw) { x0 = *(const f32x4*)(src + eo); x1 = *(const f32x4*)(src + eo + 4); }
;                 x0 += g0 * (acc[ai][bj][m][0] + b0); x1 += g1 * (acc[ai][bj][m][1] + b1); *(f32x4*)q = x0; *(f32x4*)(q + 4) = x1; } }
.Lrep_0_0_go:
	v_pk_add_f32 v[126:127], v[126:127], 0 op_sel_hi:[1,0]
	v_pk_add_f32 v[124:125], v[124:125], 0 op_sel_hi:[1,0]
	v_pk_add_f32 v[120:121], v[120:121], 0 op_sel_hi:[1,0]
	v_pk_add_f32 v[122:123], v[122:123], 0 op_sel_hi:[1,0]
	s_waitcnt vmcnt(6)
	v_pk_fma_f32 v[126:127], v[126:127], v[134:135], v[178:179]
	v_pk_fma_f32 v[124:125], v[124:125], v[132:133], v[176:177]
	v_pk_fma_f32 v[120:121], v[120:121], v[128:129], v[180:181]
	v_pk_fma_f32 v[122:123], v[122:123], v[130:131], v[182:183]
	global_store_dwordx4 v[142:143], v[124:127], off
	global_store_dwordx4 v[142:143], v[120:123], off offset:16
	v_pk_add_f32 v[118:119], v[118:119], 0 op_sel_hi:[1,0]
	v_pk_add_f32 v[116:117], v[116:117], 0 op_sel_hi:[1,0]
	v_pk_add_f32 v[112:113], v[112:113], 0 op_sel_hi:[1,0]
	v_pk_add_f32 v[114:115], v[114:115], 0 op_sel_hi:[1,0]
	s_waitcnt vmcnt(6)
	v_pk_fma_f32 v[118:119], v[118:119], v[134:135], v[186:187]
	v_pk_fma_f32 v[116:117], v[116:117], v[132:133], v[184:185]
	v_pk_fma_f32 v[112:113], v[112:113], v[128:129], v[188:189]
	v_pk_fma_f32 v[114:115], v[114:115], v[130:131], v[190:191]
	global_store_dwordx4 v[144:145], v[116:119], off
	global_store_dwordx4 v[144:145], v[112:115], off offset:16
	v_pk_add_f32 v[110:111], v[110:111], 0 op_sel_hi:[1,0]
	v_pk_add_f32 v[108:109], v[108:109], 0 op_sel_hi:[1,0]
	v_pk_add_f32 v[104:105], v[104:105], 0 op_sel_hi:[1,0]
	v_pk_add_f32 v[106:107], v[106:107], 0 op_sel_hi:[1,0]
	s_waitcnt vmcnt(6)
	v_pk_fma_f32 v[110:111], v[110:111], v[134:135], v[194:195]
	v_pk_fma_f32 v[108:109], v[108:109], v[132:133], v[192:193]
	v_pk_fma_f32 v[104:105], v[104:105], v[128:129], v[196:197]
	v_pk_fma_f32 v[106:107], v[106:107], v[130:131], v[198:199]
	global_store_dwordx4 v[158:159], v[108:111], off
	global_store_dwordx4 v[158:159], v[104:107], off offset:16
	v_pk_add_f32 v[102:103], v[102:103], 0 op_sel_hi:[1,0]
	v_pk_add_f32 v[100:101], v[100:101], 0 op_sel_hi:[1,0]
	v_pk_add_f32 v[96:97], v[96:97], 0 op_sel_hi:[1,0]
	v_pk_add_f32 v[98:99], v[98:99], 0 op_sel_hi:[1,0]
	s_waitcnt vmcnt(6)
	v_pk_fma_f32 v[102:103], v[102:103], v[134:135], v[202:203]
	v_pk_fma_f32 v[100:101], v[100:101], v[132:133], v[200:201]
	v_pk_fma_f32 v[96:97], v[96:97], v[128:129], v[204:205]
	v_pk_fma_f32 v[98:99], v[98:99], v[130:131], v[206:207]
	global_store_dwordx4 v[162:163], v[100:103], off
	global_store_dwordx4 v[162:163], v[96:99], off offset:16
	v_add_co_u32_e32 v142, vcc, 0x80000, v166
	s_nop 1
	v_addc_co_u32_e32 v143, vcc, 0, v167, vcc
	v_add_co_u32_e32 v144, vcc, 0x90000, v166
	s_nop 1
	v_addc_co_u32_e32 v145, vcc, 0, v167, vcc
	v_add_co_u32_e32 v158, vcc, 0xa0000, v166
	s_nop 1
	v_addc_co_u32_e32 v159, vcc, 0, v167, vcc
	v_add_co_u32_e32 v162, vcc, 0xb0000, v166
	s_nop 1
	v_addc_co_u32_e32 v163, vcc, 0, v167, vcc
	s_and_b64 vcc, exec, s[14:15]
	s_cbranch_vccz .Lrep_0_1_nold
	global_load_dwordx4 v[176:179], v[142:143], off
	global_load_dwordx4 v[180:183], v[142:143], off offset:16
	global_load_dwordx4 v[184:187], v[144:145], off
	global_load_dwordx4 v[188:191], v[144:145], off offset:16
	global_load_dwordx4 v[192:195], v[158:159], off
	global_load_dwordx4 v[196:199], v[158:159], off offset:16
	global_load_dwordx4 v[200:203], v[162:163], off
	global_load_dwordx4 v[204:207], v[162:163], off offset:16
	s_branch .Lrep_0_1_go

; #define EPI_LOOP_ROWS _Pragma("unroll") for (int ai = 0; ai < 2; ++ai) _Pragma("unroll") for (int m = 0; m < 4; ++m)
; #define EPI_LOOP_BJ _Pragma("unroll") for (int bj = 0; bj < 2; ++bj)
;     DI void operator()(const AccT& acc, int brow, int bcol, int wr, int wc, int fr, int fq) const {
;         EPI_LOOP_BJ { const int col = bcol + bj * 128 + wc * 32 + fq * 8;
;             const f32x4 g0 = *(const f32x4*)(gate + col), g1 = *(const f32x4*)(gate + col + 4); f32x4 b0 = (f32x4){0.f, 0.f, 0.f, 0.f}, b1 = b0; if (bias) { b0 = *(const f32x4*)(bias + col); b1 = *(const f32x4*)(bias + col + 4); }
;             EPI_LOOP_ROWS { const size_t eo = (size_t)(ai * 128 + wr * 64 + m * 16 + fr) * D + col; float* q = base + eo;
;                 f32x4 x0 = (f32x4){0.f, 0.f, 0.f, 0.f}, x1 = x0; if (rmw) { x0 = *(const f32x4*)(src + eo); x1 = *(const f32x4*)(src + eo + 4); }
;                 x0 += g0 * (acc[ai][bj][m][0] + b0); x1 += g1 * (acc[ai][bj][m][1] + b1); *(f32x4*)q = x0; *(f32x4*)(q + 4) = x1; } }
.Lrep_0_1_go:
	v_pk_add_f32 v[94:95], v[94:95], 0 op_sel_hi:[1,0]
	v_pk_add_f32 v[92:93], v[92:93], 0 op_sel_hi:[1,0]
	v_pk_add_f32 v[90:91], v[90:91], 0 op_sel_hi:[1,0]
	v_pk_add_f32 v[88:89], v[88:89], 0 op_sel_hi:[1,0]
	s_waitcnt vmcnt(6)
	v_pk_fma_f32 v[94:95], v[94:95], v[134:135], v[178:179]
	v_pk_fma_f32 v[92:93], v[92:93], v[132:133], v[176:177]
	v_pk_fma_f32 v[90:91], v[90:91], v[130:131], v[182:183]
	v_pk_fma_f32 v[88:89], v[88:89], v[128:129], v[180:181]
	global_store_dwordx4 v[142:143], v[92:95], off
	global_store_dwordx4 v[142:143], v[88:91], off offset:16
	v_pk_add_f32 v[86:87], v[86:87], 0 op_sel_hi:[1,0]
	v_pk_add_f32 v[84:85], v[84:85], 0 op_sel_hi:[1,0]
	v_pk_add_f32 v[80:81], v[80:81], 0 op_sel_hi:[1,0]
	v_pk_add_f32 v[82:83], v[82:83], 0 op_sel_hi:[1,0]
	s_waitcnt vmcnt(6)
	v_pk_fma_f32 v[86:87], v[86:87], v[134:135], v[186:187]
	v_pk_fma_f32 v[84:85], v[84:85], v[132:133], v[184:185]
	v_pk_fma_f32 v[80:81], v[80:81], v[128:129], v[188:189]
	v_pk_fma_f32 v[82:83], v[82:83], v[130:131], v[190:191]
	global_store_dwordx4 v[144:145], v[84:87], off
	global_store_dwordx4 v[144:145], v[80:83], off offset:16
	v_pk_add_f32 v[74:75], v[74:75], 0 op_sel_hi:[1,0]
	v_pk_add_f32 v[78:79], v[78:79], 0 op_sel_hi:[1,0]
	v_pk_add_f32 v[76:77], v[76:77], 0 op_sel_hi:[1,0]
	v_pk_add_f32 v[72:73], v[72:73], 0 op_sel_hi:[1,0]
	s_waitcnt vmcnt(6)
	v_pk_fma_f32 v[74:75], v[74:75], v[130:131], v[198:199]
	v_pk_fma_f32 v[78:79], v[78:79], v[134:135], v[194:195]
	v_pk_fma_f32 v[76:77], v[76:77], v[132:133], v[192:193]
	v_pk_fma_f32 v[72:73], v[72:73], v[128:129], v[196:197]
	global_store_dwordx4 v[158:159], v[76:79], off
	global_store_dwordx4 v[158:159], v[72:75], off offset:16
	v_pk_add_f32 v[70:71], v[70:71], 0 op_sel_hi:[1,0]
	v_pk_add_f32 v[68:69], v[68:69], 0 op_sel_hi:[1,0]
	v_pk_add_f32 v[66:67], v[66:67], 0 op_sel_hi:[1,0]
	v_pk_add_f32 v[64:65], v[64:65], 0 op_sel_hi:[1,0]
	s_waitcnt vmcnt(6)
	v_pk_fma_f32 v[70:71], v[70:71], v[134:135], v[202:203]
	v_pk_fma_f32 v[68:69], v[68:69], v[132:133], v[200:201]
	v_pk_fma_f32 v[66:67], v[66:67], v[130:131], v[206:207]
	v_pk_fma_f32 v[64:65], v[64:65], v[128:129], v[204:205]
	global_store_dwordx4 v[162:163], v[68:71], off
	global_store_dwordx4 v[162:163], v[64:67], off offset:16
	v_add_co_u32_e32 v142, vcc, 0x200, v166
	s_nop 1
	v_addc_co_u32_e32 v143, vcc, 0, v167, vcc
	v_add_co_u32_e32 v144, vcc, 0x10200, v166
	s_nop 1
	v_addc_co_u32_e32 v145, vcc, 0, v167, vcc
	v_add_co_u32_e32 v158, vcc, 0x20200, v166
	s_nop 1
	v_addc_co_u32_e32 v159, vcc, 0, v167, vcc
	v_add_co_u32_e32 v162, vcc, 0x30200, v166
	s_nop 1
	v_addc_co_u32_e32 v163, vcc, 0, v167, vcc
	s_and_b64 vcc, exec, s[14:15]
	s_cbranch_vccz .Lrep_0_2_nold
	global_load_dwordx4 v[176:179], v[142:143], off
	global_load_dwordx4 v[180:183], v[142:143], off offset:16
	global_load_dwordx4 v[184:187], v[144:145], off
	global_load_dwordx4 v[188:191], v[144:145], off offset:16
	global_load_dwordx4 v[192:195], v[158:159], off
	global_load_dwordx4 v[196:199], v[158:159], off offset:16
	global_load_dwordx4 v[200:203], v[162:163], off
	global_load_dwordx4 v[204:207], v[162:163], off offset:16
	s_branch .Lrep_0_2_go

; #define EPI_LOOP_ROWS _Pragma("unroll") for (int ai = 0; ai < 2; ++ai) _Pragma("unroll") for (int m = 0; m < 4; ++m)
; #define EPI_LOOP_BJ _Pragma("unroll") for (int bj = 0; bj < 2; ++bj)
;     DI void operator()(const AccT& acc, int brow, int bcol, int wr, int wc, int fr, int fq) const {
;         EPI_LOOP_BJ { const int col = bcol + bj * 128 + wc * 32 + fq * 8;
;             const f32x4 g0 = *(const f32x4*)(gate + col), g1 = *(const f32x4*)(gate + col + 4); f32x4 b0 = (f32x4){0.f, 0.f, 0.f, 0.f}, b1 = b0; if (bias) { b0 = *(const f32x4*)(bias + col); b1 = *(const f32x4*)(bias + col + 4); }
;             EPI_LOOP_ROWS { const size_t eo = (size_t)(ai * 128 + wr * 64 + m * 16 + fr) * D + col; float* q = base + eo;
;                 f32x4 x0 = (f32x4){0.f, 0.f, 0.f, 0.f}, x1 = x0; if (rmw) { x0 = *(const f32x4*)(src + eo); x1 = *(const f32x4*)(src + eo + 4); }
;                 x0 += g0 * (acc[ai][bj][m][0] + b0); x1 += g1 * (acc[ai][bj][m][1] + b1); *(f32x4*)q = x0; *(f32x4*)(q + 4) = x1; } }
.Lrep_0_2_go:
	v_pk_add_f32 v[62:63], v[62:63], 0 op_sel_hi:[1,0]
	v_pk_add_f32 v[60:61], v[60:61], 0 op_sel_hi:[1,0]
	v_pk_add_f32 v[58:59], v[58:59], 0 op_sel_hi:[1,0]
	v_pk_add_f32 v[56:57], v[56:57], 0 op_sel_hi:[1,0]
	s_waitcnt vmcnt(6)
	v_pk_fma_f32 v[62:63], v[62:63], v[138:139], v[178:179]
	v_pk_fma_f32 v[60:61], v[60:61], v[136:137], v[176:177]
	v_pk_fma_f32 v[58:59], v[58:59], v[174:175], v[182:183]
	v_pk_fma_f32 v[56:57], v[56:57], v[172:173], v[180:181]
	global_store_dwordx4 v[142:143], v[60:63], off
	global_store_dwordx4 v[142:143], v[56:59], off offset:16
	v_pk_add_f32 v[54:55], v[54:55], 0 op_sel_hi:[1,0]
	v_pk_add_f32 v[52:53], v[52:53], 0 op_sel_hi:[1,0]
	v_pk_add_f32 v[50:51], v[50:51], 0 op_sel_hi:[1,0]
	v_pk_add_f32 v[48:49], v[48:49], 0 op_sel_hi:[1,0]
	s_waitcnt vmcnt(6)
	v_pk_fma_f32 v[54:55], v[54:55], v[138:139], v[186:187]
	v_pk_fma_f32 v[52:53], v[52:53], v[136:137], v[184:185]
	v_pk_fma_f32 v[50:51], v[50:51], v[174:175], v[190:191]
	v_pk_fma_f32 v[48:49], v[48:49], v[172:173], v[188:189]
	global_store_dwordx4 v[144:145], v[52:55], off
	global_store_dwordx4 v[144:145], v[48:51], off offset:16
	v_pk_add_f32 v[46:47], v[46:47], 0 op_sel_hi:[1,0]
	v_pk_add_f32 v[44:45], v[44:45], 0 op_sel_hi:[1,0]
	v_pk_add_f32 v[42:43], v[42:43], 0 op_sel_hi:[1,0]
	v_pk_add_f32 v[40:41], v[40:41], 0 op_sel_hi:[1,0]
	s_waitcnt vmcnt(6)
	v_pk_fma_f32 v[46:47], v[46:47], v[138:139], v[194:195]
	v_pk_fma_f32 v[44:45], v[44:45], v[136:137], v[192:193]
	v_pk_fma_f32 v[42:43], v[42:43], v[174:175], v[198:199]
	v_pk_fma_f32 v[40:41], v[40:41], v[172:173], v[196:197]
	global_store_dwordx4 v[158:159], v[44:47], off
	global_store_dwordx4 v[158:159], v[40:43], off offset:16
	v_pk_add_f32 v[38:39], v[38:39], 0 op_sel_hi:[1,0]
	v_pk_add_f32 v[36:37], v[36:37], 0 op_sel_hi:[1,0]
	v_pk_add_f32 v[34:35], v[34:35], 0 op_sel_hi:[1,0]
	v_pk_add_f32 v[32:33], v[32:33], 0 op_sel_hi:[1,0]
	s_waitcnt vmcnt(6)
	v_pk_fma_f32 v[38:39], v[38:39], v[138:139], v[202:203]
	v_pk_fma_f32 v[36:37], v[36:37], v[136:137], v[200:201]
	v_pk_fma_f32 v[34:35], v[34:35], v[174:175], v[206:207]
	v_pk_fma_f32 v[32:33], v[32:33], v[172:173], v[204:205]
	global_store_dwordx4 v[162:163], v[36:39], off
	global_store_dwordx4 v[162:163], v[32:35], off offset:16
	v_add_co_u32_e32 v142, vcc, 0x80200, v166
	s_nop 1
	v_addc_co_u32_e32 v143, vcc, 0, v167, vcc
	v_add_co_u32_e32 v144, vcc, 0x90200, v166
	s_nop 1
	v_addc_co_u32_e32 v145, vcc, 0, v167, vcc
	v_add_co_u32_e32 v158, vcc, 0xa0200, v166
	s_nop 1
	v_addc_co_u32_e32 v159, vcc, 0, v167, vcc
	v_add_co_u32_e32 v162, vcc, 0xb0200, v166
	s_nop 1
	v_addc_co_u32_e32 v163, vcc, 0, v167, vcc
	s_and_b64 vcc, exec, s[14:15]
	s_cbranch_vccz .Lrep_0_3_nold
	global_load_dwordx4 v[176:179], v[142:143], off
	global_load_dwordx4 v[180:183], v[142:143], off offset:16
	global_load_dwordx4 v[184:187], v[144:145], off
	global_load_dwordx4 v[188:191], v[144:145], off offset:16
	global_load_dwordx4 v[192:195], v[158:159], off
	global_load_dwordx4 v[196:199], v[158:159], off offset:16
	global_load_dwordx4 v[200:203], v[162:163], off
	global_load_dwordx4 v[204:207], v[162:163], off offset:16
	s_branch .Lrep_0_3_go

; #define BAR __builtin_amdgcn_s_barrier()
; #define EPI_LOOP_ROWS _Pragma("unroll") for (int ai = 0; ai < 2; ++ai) _Pragma("unroll") for (int m = 0; m < 4; ++m)
; #define EPI_LOOP_BJ _Pragma("unroll") for (int bj = 0; bj < 2; ++bj)
; template <class Get, class Epi>
; DI void gemm_loop(int ntiles, int ld, char* shm, const Get& get, const Epi& epi) {
;     ...
;         if (!has_next) break;
;         G_ZERO;
;         cur = nxt; cA = nA; cB = nB; L = Ln;
;         if (wr == 1) BAR;
;     DI void operator()(const AccT& acc, int brow, int bcol, int wr, int wc, int fr, int fq) const {
;         EPI_LOOP_BJ { const int col = bcol + bj * 128 + wc * 32 + fq * 8;
;             const f32x4 g0 = *(const f32x4*)(gate + col), g1 = *(const f32x4*)(gate + col + 4); f32x4 b0 = (f32x4){0.f, 0.f, 0.f, 0.f}, b1 = b0; if (bias) { b0 = *(const f32x4*)(bias + col); b1 = *(const f32x4*)(bias + col + 4); }
;             EPI_LOOP_ROWS { const size_t eo = (size_t)(ai * 128 + wr * 64 + m * 16 + fr) * D + col; float* q = base + eo;
;                 f32x4 x0 = (f32x4){0.f, 0.f, 0.f, 0.f}, x1 = x0; if (rmw) { x0 = *(const f32x4*)(src + eo); x1 = *(const f32x4*)(src + eo + 4); }
;                 x0 += g0 * (acc[ai][bj][m][0] + b0); x1 += g1 * (acc[ai][bj][m][1] + b1); *(f32x4*)q = x0; *(f32x4*)(q + 4) = x1; } }
.Lrep_0_3_go:
	v_pk_add_f32 v[30:31], v[30:31], 0 op_sel_hi:[1,0]
	v_pk_add_f32 v[28:29], v[28:29], 0 op_sel_hi:[1,0]
	v_pk_add_f32 v[26:27], v[26:27], 0 op_sel_hi:[1,0]
	v_pk_add_f32 v[24:25], v[24:25], 0 op_sel_hi:[1,0]
	s_waitcnt vmcnt(6)
	v_pk_fma_f32 v[30:31], v[30:31], v[138:139], v[178:179]
	v_pk_fma_f32 v[28:29], v[28:29], v[136:137], v[176:177]
	v_pk_fma_f32 v[26:27], v[26:27], v[174:175], v[182:183]
	v_pk_fma_f32 v[24:25], v[24:25], v[172:173], v[180:181]
	global_store_dwordx4 v[142:143], v[28:31], off
	global_store_dwordx4 v[142:143], v[24:27], off offset:16
	v_pk_add_f32 v[22:23], v[22:23], 0 op_sel_hi:[1,0]
	v_pk_add_f32 v[20:21], v[20:21], 0 op_sel_hi:[1,0]
	v_pk_add_f32 v[18:19], v[18:19], 0 op_sel_hi:[1,0]
	v_pk_add_f32 v[16:17], v[16:17], 0 op_sel_hi:[1,0]
	s_waitcnt vmcnt(6)
	v_pk_fma_f32 v[22:23], v[22:23], v[138:139], v[186:187]
	v_pk_fma_f32 v[20:21], v[20:21], v[136:137], v[184:185]
	v_pk_fma_f32 v[18:19], v[18:19], v[174:175], v[190:191]
	v_pk_fma_f32 v[16:17], v[16:17], v[172:173], v[188:189]
	global_store_dwordx4 v[144:145], v[20:23], off
	global_store_dwordx4 v[144:145], v[16:19], off offset:16
	v_pk_add_f32 v[14:15], v[14:15], 0 op_sel_hi:[1,0]
	v_pk_add_f32 v[12:13], v[12:13], 0 op_sel_hi:[1,0]
	v_pk_add_f32 v[8:9], v[8:9], 0 op_sel_hi:[1,0]
	v_pk_add_f32 v[10:11], v[10:11], 0 op_sel_hi:[1,0]
	s_waitcnt vmcnt(6)
	v_pk_fma_f32 v[14:15], v[14:15], v[138:139], v[194:195]
	v_pk_fma_f32 v[12:13], v[12:13], v[136:137], v[192:193]
	v_pk_fma_f32 v[8:9], v[8:9], v[172:173], v[196:197]
	v_pk_fma_f32 v[10:11], v[10:11], v[174:175], v[198:199]
	global_store_dwordx4 v[158:159], v[12:15], off
	global_store_dwordx4 v[158:159], v[8:11], off offset:16
	v_pk_add_f32 v[6:7], v[6:7], 0 op_sel_hi:[1,0]
	v_pk_add_f32 v[4:5], v[4:5], 0 op_sel_hi:[1,0]
	v_pk_add_f32 v[2:3], v[2:3], 0 op_sel_hi:[1,0]
	v_pk_add_f32 v[0:1], v[0:1], 0 op_sel_hi:[1,0]
	s_waitcnt vmcnt(6)
	v_pk_fma_f32 v[6:7], v[6:7], v[138:139], v[202:203]
	v_pk_fma_f32 v[4:5], v[4:5], v[136:137], v[200:201]
	v_pk_fma_f32 v[2:3], v[2:3], v[174:175], v[206:207]
	v_pk_fma_f32 v[0:1], v[0:1], v[172:173], v[204:205]
	global_store_dwordx4 v[162:163], v[4:7], off
	global_store_dwordx4 v[162:163], v[0:3], off offset:16
	s_and_b64 vcc, exec, s[2:3]
	s_mov_b64 s[2:3], -1
	s_cbranch_vccnz .LBB0_835
	s_andn2_b64 vcc, exec, s[8:9]
	s_cbranch_vccnz .LBB0_834
	s_barrier
	s_branch .LBB0_834

; #define EPI_LOOP_ROWS _Pragma("unroll") for (int ai = 0; ai < 2; ++ai) _Pragma("unroll") for (int m = 0; m < 4; ++m)
; #define EPI_LOOP_BJ _Pragma("unroll") for (int bj = 0; bj < 2; ++bj)
;     DI void operator()(const AccT& acc, int brow, int bcol, int wr, int wc, int fr, int fq) const {
;         EPI_LOOP_BJ { const int col = bcol + bj * 128 + wc * 32 + fq * 8;
;             const f32x4 g0 = *(const f32x4*)(gate + col), g1 = *(const f32x4*)(gate + col + 4); f32x4 b0 = (f32x4){0.f, 0.f, 0.f, 0.f}, b1 = b0; if (bias) { b0 = *(const f32x4*)(bias + col); b1 = *(const f32x4*)(bias + col + 4); }
;             EPI_LOOP_ROWS { const size_t eo = (size_t)(ai * 128 + wr * 64 + m * 16 + fr) * D + col; float* q = base + eo;
;                 f32x4 x0 = (f32x4){0.f, 0.f, 0.f, 0.f}, x1 = x0; if (rmw) { x0 = *(const f32x4*)(src + eo); x1 = *(const f32x4*)(src + eo + 4); }
.LBB0_1470:
	v_lshrrev_b32_e32 v128, 1, v136
	v_and_b32_e32 v129, 0x60, v128
	v_and_b32_e32 v128, 24, v128
	v_add3_u32 v158, v129, s2, v128
	v_ashrrev_i32_e32 v159, 31, v158
	v_lshlrev_b64 v[138:139], 2, v[158:159]
	v_lshl_add_u64 v[160:161], s[46:47], 0, v[138:139]
	global_load_dwordx4 v[128:131], v[160:161], off offset:16
	global_load_dwordx4 v[132:135], v[160:161], off
	v_and_b32_e32 v137, 15, v136
	v_ashrrev_i32_e32 v136, 2, v136
	s_movk_i32 s2, 0xffc0
	v_and_or_b32 v164, v136, s2, v137
	v_ashrrev_i32_e32 v165, 31, v164
	v_lshlrev_b64 v[136:137], 12, v[164:165]
	v_lshl_add_u64 v[162:163], s[48:49], 0, v[136:137]
	v_cndmask_b32_e64 v137, 0, 1, s[14:15]
	v_lshl_add_u64 v[166:167], v[162:163], 0, v[138:139]
	v_mov_b32_e32 v136, 0
	v_cmp_ne_u32_e64 s[2:3], 1, v137
	global_load_dwordx4 v[172:175], v[160:161], off offset:528
	global_load_dwordx4 v[136:139], v[160:161], off offset:512
	v_mov_b32_e32 v142, v166
	v_mov_b32_e32 v143, v167
	v_add_co_u32_e32 v144, vcc, 0x10000, v166
	s_nop 1
	v_addc_co_u32_e32 v145, vcc, 0, v167, vcc
	v_add_co_u32_e32 v158, vcc, 0x20000, v166
	s_nop 1
	v_addc_co_u32_e32 v159, vcc, 0, v167, vcc
	v_add_co_u32_e32 v162, vcc, 0x30000, v166
	s_nop 1
	v_addc_co_u32_e32 v163, vcc, 0, v167, vcc
	s_and_b64 vcc, exec, s[14:15]
	s_cbranch_vccz .Lrep_1_0_nold
	global_load_dwordx4 v[176:179], v[142:143], off
	global_load_dwordx4 v[180:183], v[142:143], off offset:16
	global_load_dwordx4 v[184:187], v[144:145], off
	global_load_dwordx4 v[188:191], v[144:145], off offset:16
	global_load_dwordx4 v[192:195], v[158:159], off
	global_load_dwordx4 v[196:199], v[158:159], off offset:16
	global_load_dwordx4 v[200:203], v[162:163], off
	global_load_dwordx4 v[204:207], v[162:163], off offset:16
	s_branch .Lrep_1_0_go

; #define BAR __builtin_amdgcn_s_barrier()
; #define EPI_LOOP_ROWS _Pragma("unroll") for (int ai = 0; ai < 2; ++ai) _Pragma("unroll") for (int m = 0; m < 4; ++m)
; #define EPI_LOOP_BJ _Pragma("unroll") for (int bj = 0; bj < 2; ++bj)
; template <class Get, class Epi>
; DI void gemm_loop(int ntiles, int ld, char* shm, const Get& get, const Epi& epi) {
;     ...
;         if (!has_next) break;
;         G_ZERO;
;         cur = nxt; cA = nA; cB = nB; L = Ln;
;         if (wr == 1) BAR;
;     DI void operator()(const AccT& acc, int brow, int bcol, int wr, int wc, int fr, int fq) const {
;         EPI_LOOP_BJ { const int col = bcol + bj * 128 + wc * 32 + fq * 8;
;             const f32x4 g0 = *(const f32x4*)(gate + col), g1 = *(const f32x4*)(gate + col + 4); f32x4 b0 = (f32x4){0.f, 0.f, 0.f, 0.f}, b1 = b0; if (bias) { b0 = *(const f32x4*)(bias + col); b1 = *(const f32x4*)(bias + col + 4); }
;             EPI_LOOP_ROWS { const size_t eo = (size_t)(ai * 128 + wr * 64 + m * 16 + fr) * D + col; float* q = base + eo;
;                 f32x4 x0 = (f32x4){0.f, 0.f, 0.f, 0.f}, x1 = x0; if (rmw) { x0 = *(const f32x4*)(src + eo); x1 = *(const f32x4*)(src + eo + 4); }
;                 x0 += g0 * (acc[ai][bj][m][0] + b0); x1 += g1 * (acc[ai][bj][m][1] + b1); *(f32x4*)q = x0; *(f32x4*)(q + 4) = x1; } }
.Lrep_1_3_go:
	v_pk_add_f32 v[30:31], v[30:31], 0 op_sel_hi:[1,0]
	v_pk_add_f32 v[28:29], v[28:29], 0 op_sel_hi:[1,0]
	v_pk_add_f32 v[26:27], v[26:27], 0 op_sel_hi:[1,0]
	v_pk_add_f32 v[24:25], v[24:25], 0 op_sel_hi:[1,0]
	s_waitcnt vmcnt(6)
	v_pk_fma_f32 v[30:31], v[30:31], v[138:139], v[178:179]
	v_pk_fma_f32 v[28:29], v[28:29], v[136:137], v[176:177]
	v_pk_fma_f32 v[26:27], v[26:27], v[174:175], v[182:183]
	v_pk_fma_f32 v[24:25], v[24:25], v[172:173], v[180:181]
	global_store_dwordx4 v[142:143], v[28:31], off
	global_store_dwordx4 v[142:143], v[24:27], off offset:16
	v_pk_add_f32 v[22:23], v[22:23], 0 op_sel_hi:[1,0]
	v_pk_add_f32 v[20:21], v[20:21], 0 op_sel_hi:[1,0]
	v_pk_add_f32 v[18:19], v[18:19], 0 op_sel_hi:[1,0]
	v_pk_add_f32 v[16:17], v[16:17], 0 op_sel_hi:[1,0]
	s_waitcnt vmcnt(6)
	v_pk_fma_f32 v[22:23], v[22:23], v[138:139], v[186:187]
	v_pk_fma_f32 v[20:21], v[20:21], v[136:137], v[184:185]
	v_pk_fma_f32 v[18:19], v[18:19], v[174:175], v[190:191]
	v_pk_fma_f32 v[16:17], v[16:17], v[172:173], v[188:189]
	global_store_dwordx4 v[144:145], v[20:23], off
	global_store_dwordx4 v[144:145], v[16:19], off offset:16
	v_pk_add_f32 v[14:15], v[14:15], 0 op_sel_hi:[1,0]
	v_pk_add_f32 v[12:13], v[12:13], 0 op_sel_hi:[1,0]
	v_pk_add_f32 v[8:9], v[8:9], 0 op_sel_hi:[1,0]
	v_pk_add_f32 v[10:11], v[10:11], 0 op_sel_hi:[1,0]
	s_waitcnt vmcnt(6)
	v_pk_fma_f32 v[14:15], v[14:15], v[138:139], v[194:195]
	v_pk_fma_f32 v[12:13], v[12:13], v[136:137], v[192:193]
	v_pk_fma_f32 v[8:9], v[8:9], v[172:173], v[196:197]
	v_pk_fma_f32 v[10:11], v[10:11], v[174:175], v[198:199]
	global_store_dwordx4 v[158:159], v[12:15], off
	global_store_dwordx4 v[158:159], v[8:11], off offset:16
	v_pk_add_f32 v[6:7], v[6:7], 0 op_sel_hi:[1,0]
	v_pk_add_f32 v[4:5], v[4:5], 0 op_sel_hi:[1,0]
	v_pk_add_f32 v[2:3], v[2:3], 0 op_sel_hi:[1,0]
	v_pk_add_f32 v[0:1], v[0:1], 0 op_sel_hi:[1,0]
	s_waitcnt vmcnt(6)
	v_pk_fma_f32 v[6:7], v[6:7], v[138:139], v[202:203]
	v_pk_fma_f32 v[4:5], v[4:5], v[136:137], v[200:201]
	v_pk_fma_f32 v[2:3], v[2:3], v[174:175], v[206:207]
	v_pk_fma_f32 v[0:1], v[0:1], v[172:173], v[204:205]
	global_store_dwordx4 v[162:163], v[4:7], off
	global_store_dwordx4 v[162:163], v[0:3], off offset:16
	s_andn2_b64 vcc, exec, s[34:35]
	s_mov_b64 s[2:3], -1
	s_cbranch_vccnz .LBB0_1452
	s_andn2_b64 vcc, exec, s[8:9]
	s_cbranch_vccnz .LBB0_1451
	s_barrier
	s_branch .LBB0_1451

; #define EPI_LOOP_ROWS _Pragma("unroll") for (int ai = 0; ai < 2; ++ai) _Pragma("unroll") for (int m = 0; m < 4; ++m)
; #define EPI_LOOP_BJ _Pragma("unroll") for (int bj = 0; bj < 2; ++bj)
;     DI void operator()(const AccT& acc, int brow, int bcol, int wr, int wc, int fr, int fq) const {
;         EPI_LOOP_BJ { const int col = bcol + bj * 128 + wc * 32 + fq * 8;
;             const f32x4 g0 = *(const f32x4*)(gate + col), g1 = *(const f32x4*)(gate + col + 4); f32x4 b0 = (f32x4){0.f, 0.f, 0.f, 0.f}, b1 = b0; if (bias) { b0 = *(const f32x4*)(bias + col); b1 = *(const f32x4*)(bias + col + 4); }
;             EPI_LOOP_ROWS { const size_t eo = (size_t)(ai * 128 + wr * 64 + m * 16 + fr) * D + col; float* q = base + eo;
;                 f32x4 x0 = (f32x4){0.f, 0.f, 0.f, 0.f}, x1 = x0; if (rmw) { x0 = *(const f32x4*)(src + eo); x1 = *(const f32x4*)(src + eo + 4); }
.LBB0_1788:
	v_lshrrev_b32_e32 v128, 1, v136
	v_and_b32_e32 v129, 0x60, v128
	v_and_b32_e32 v128, 24, v128
	v_add3_u32 v158, v129, s71, v128
	v_ashrrev_i32_e32 v159, 31, v158
	v_lshlrev_b64 v[138:139], 2, v[158:159]
	v_lshl_add_u64 v[160:161], s[4:5], 0, v[138:139]
	global_load_dwordx4 v[128:131], v[160:161], off offset:16
	global_load_dwordx4 v[132:135], v[160:161], off
	v_and_b32_e32 v137, 15, v136
	v_ashrrev_i32_e32 v136, 2, v136
	s_movk_i32 s4, 0xffc0
	v_and_or_b32 v164, v136, s4, v137
	v_ashrrev_i32_e32 v165, 31, v164
	v_lshlrev_b64 v[136:137], 12, v[164:165]
	v_lshl_add_u64 v[162:163], s[40:41], 0, v[136:137]
	v_cndmask_b32_e64 v137, 0, 1, s[14:15]
	v_lshl_add_u64 v[166:167], v[162:163], 0, v[138:139]
	v_mov_b32_e32 v136, 0
	v_cmp_ne_u32_e64 s[4:5], 1, v137
	global_load_dwordx4 v[172:175], v[160:161], off offset:528
	global_load_dwordx4 v[136:139], v[160:161], off offset:512
	v_mov_b32_e32 v142, v166
	v_mov_b32_e32 v143, v167
	v_add_co_u32_e32 v144, vcc, 0x10000, v166
	s_nop 1
	v_addc_co_u32_e32 v145, vcc, 0, v167, vcc
	v_add_co_u32_e32 v158, vcc, 0x20000, v166
	s_nop 1
	v_addc_co_u32_e32 v159, vcc, 0, v167, vcc
	v_add_co_u32_e32 v162, vcc, 0x30000, v166
	s_nop 1
	v_addc_co_u32_e32 v163, vcc, 0, v167, vcc
	s_and_b64 vcc, exec, s[14:15]
	s_cbranch_vccz .Lrep_2_0_nold
	global_load_dwordx4 v[176:179], v[142:143], off
	global_load_dwordx4 v[180:183], v[142:143], off offset:16
	global_load_dwordx4 v[184:187], v[144:145], off
	global_load_dwordx4 v[188:191], v[144:145], off offset:16
	global_load_dwordx4 v[192:195], v[158:159], off
	global_load_dwordx4 v[196:199], v[158:159], off offset:16
	global_load_dwordx4 v[200:203], v[162:163], off
	global_load_dwordx4 v[204:207], v[162:163], off offset:16
	s_branch .Lrep_2_0_go

; #define EPI_LOOP_ROWS _Pragma("unroll") for (int ai = 0; ai < 2; ++ai) _Pragma("unroll") for (int m = 0; m < 4; ++m)
; #define EPI_LOOP_BJ _Pragma("unroll") for (int bj = 0; bj < 2; ++bj)
;     DI void operator()(const AccT& acc, int brow, int bcol, int wr, int wc, int fr, int fq) const {
;         EPI_LOOP_BJ { const int col = bcol + bj * 128 + wc * 32 + fq * 8;
;             const f32x4 g0 = *(const f32x4*)(gate + col), g1 = *(const f32x4*)(gate + col + 4); f32x4 b0 = (f32x4){0.f, 0.f, 0.f, 0.f}, b1 = b0; if (bias) { b0 = *(const f32x4*)(bias + col); b1 = *(const f32x4*)(bias + col + 4); }
;             EPI_LOOP_ROWS { const size_t eo = (size_t)(ai * 128 + wr * 64 + m * 16 + fr) * D + col; float* q = base + eo;
;                 f32x4 x0 = (f32x4){0.f, 0.f, 0.f, 0.f}, x1 = x0; if (rmw) { x0 = *(const f32x4*)(src + eo); x1 = *(const f32x4*)(src + eo + 4); }
.LBB0_2581:
	v_lshrrev_b32_e32 v128, 1, v136
	v_and_b32_e32 v129, 0x60, v128
	v_and_b32_e32 v128, 24, v128
	v_add3_u32 v158, v129, s2, v128
	v_ashrrev_i32_e32 v159, 31, v158
	v_lshlrev_b64 v[138:139], 2, v[158:159]
	v_lshl_add_u64 v[160:161], s[46:47], 0, v[138:139]
	global_load_dwordx4 v[128:131], v[160:161], off offset:16
	global_load_dwordx4 v[132:135], v[160:161], off
	v_and_b32_e32 v137, 15, v136
	v_ashrrev_i32_e32 v136, 2, v136
	s_movk_i32 s2, 0xffc0
	v_and_or_b32 v164, v136, s2, v137
	v_ashrrev_i32_e32 v165, 31, v164
	v_lshlrev_b64 v[136:137], 12, v[164:165]
	v_lshl_add_u64 v[162:163], s[52:53], 0, v[136:137]
	v_cndmask_b32_e64 v137, 0, 1, s[14:15]
	v_lshl_add_u64 v[166:167], v[162:163], 0, v[138:139]
	v_mov_b32_e32 v136, 0
	v_cmp_ne_u32_e64 s[2:3], 1, v137
	global_load_dwordx4 v[172:175], v[160:161], off offset:528
	global_load_dwordx4 v[136:139], v[160:161], off offset:512
	v_mov_b32_e32 v142, v166
	v_mov_b32_e32 v143, v167
	v_add_co_u32_e32 v144, vcc, 0x10000, v166
	s_nop 1
	v_addc_co_u32_e32 v145, vcc, 0, v167, vcc
	v_add_co_u32_e32 v158, vcc, 0x20000, v166
	s_nop 1
	v_addc_co_u32_e32 v159, vcc, 0, v167, vcc
	v_add_co_u32_e32 v162, vcc, 0x30000, v166
	s_nop 1
	v_addc_co_u32_e32 v163, vcc, 0, v167, vcc
	s_and_b64 vcc, exec, s[14:15]
	s_cbranch_vccz .Lrep_3_0_nold
	global_load_dwordx4 v[176:179], v[142:143], off
	global_load_dwordx4 v[180:183], v[142:143], off offset:16
	global_load_dwordx4 v[184:187], v[144:145], off
	global_load_dwordx4 v[188:191], v[144:145], off offset:16
	global_load_dwordx4 v[192:195], v[158:159], off
	global_load_dwordx4 v[196:199], v[158:159], off offset:16
	global_load_dwordx4 v[200:203], v[162:163], off
	global_load_dwordx4 v[204:207], v[162:163], off offset:16
	s_branch .Lrep_3_0_go

; #define BAR __builtin_amdgcn_s_barrier()
; #define EPI_LOOP_ROWS _Pragma("unroll") for (int ai = 0; ai < 2; ++ai) _Pragma("unroll") for (int m = 0; m < 4; ++m)
; #define EPI_LOOP_BJ _Pragma("unroll") for (int bj = 0; bj < 2; ++bj)
; template <class Get, class Epi>
; DI void gemm_loop(int ntiles, int ld, char* shm, const Get& get, const Epi& epi) {
;     ...
;         if (!has_next) break;
;         G_ZERO;
;         cur = nxt; cA = nA; cB = nB; L = Ln;
;         if (wr == 1) BAR;
;     DI void operator()(const AccT& acc, int brow, int bcol, int wr, int wc, int fr, int fq) const {
;         EPI_LOOP_BJ { const int col = bcol + bj * 128 + wc * 32 + fq * 8;
;             const f32x4 g0 = *(const f32x4*)(gate + col), g1 = *(const f32x4*)(gate + col + 4); f32x4 b0 = (f32x4){0.f, 0.f, 0.f, 0.f}, b1 = b0; if (bias) { b0 = *(const f32x4*)(bias + col); b1 = *(const f32x4*)(bias + col + 4); }
;             EPI_LOOP_ROWS { const size_t eo = (size_t)(ai * 128 + wr * 64 + m * 16 + fr) * D + col; float* q = base + eo;
;                 f32x4 x0 = (f32x4){0.f, 0.f, 0.f, 0.f}, x1 = x0; if (rmw) { x0 = *(const f32x4*)(src + eo); x1 = *(const f32x4*)(src + eo + 4); }
;                 x0 += g0 * (acc[ai][bj][m][0] + b0); x1 += g1 * (acc[ai][bj][m][1] + b1); *(f32x4*)q = x0; *(f32x4*)(q + 4) = x1; } }
.Lrep_3_3_go:
	v_pk_add_f32 v[30:31], v[30:31], 0 op_sel_hi:[1,0]
	v_pk_add_f32 v[28:29], v[28:29], 0 op_sel_hi:[1,0]
	v_pk_add_f32 v[26:27], v[26:27], 0 op_sel_hi:[1,0]
	v_pk_add_f32 v[24:25], v[24:25], 0 op_sel_hi:[1,0]
	s_waitcnt vmcnt(6)
	v_pk_fma_f32 v[30:31], v[30:31], v[138:139], v[178:179]
	v_pk_fma_f32 v[28:29], v[28:29], v[136:137], v[176:177]
	v_pk_fma_f32 v[26:27], v[26:27], v[174:175], v[182:183]
	v_pk_fma_f32 v[24:25], v[24:25], v[172:173], v[180:181]
	global_store_dwordx4 v[142:143], v[28:31], off
	global_store_dwordx4 v[142:143], v[24:27], off offset:16
	v_pk_add_f32 v[22:23], v[22:23], 0 op_sel_hi:[1,0]
	v_pk_add_f32 v[20:21], v[20:21], 0 op_sel_hi:[1,0]
	v_pk_add_f32 v[18:19], v[18:19], 0 op_sel_hi:[1,0]
	v_pk_add_f32 v[16:17], v[16:17], 0 op_sel_hi:[1,0]
	s_waitcnt vmcnt(6)
	v_pk_fma_f32 v[22:23], v[22:23], v[138:139], v[186:187]
	v_pk_fma_f32 v[20:21], v[20:21], v[136:137], v[184:185]
	v_pk_fma_f32 v[18:19], v[18:19], v[174:175], v[190:191]
	v_pk_fma_f32 v[16:17], v[16:17], v[172:173], v[188:189]
	global_store_dwordx4 v[144:145], v[20:23], off
	global_store_dwordx4 v[144:145], v[16:19], off offset:16
	v_pk_add_f32 v[14:15], v[14:15], 0 op_sel_hi:[1,0]
	v_pk_add_f32 v[12:13], v[12:13], 0 op_sel_hi:[1,0]
	v_pk_add_f32 v[8:9], v[8:9], 0 op_sel_hi:[1,0]
	v_pk_add_f32 v[10:11], v[10:11], 0 op_sel_hi:[1,0]
	s_waitcnt vmcnt(6)
	v_pk_fma_f32 v[14:15], v[14:15], v[138:139], v[194:195]
	v_pk_fma_f32 v[12:13], v[12:13], v[136:137], v[192:193]
	v_pk_fma_f32 v[8:9], v[8:9], v[172:173], v[196:197]
	v_pk_fma_f32 v[10:11], v[10:11], v[174:175], v[198:199]
	global_store_dwordx4 v[158:159], v[12:15], off
	global_store_dwordx4 v[158:159], v[8:11], off offset:16
	v_pk_add_f32 v[6:7], v[6:7], 0 op_sel_hi:[1,0]
	v_pk_add_f32 v[4:5], v[4:5], 0 op_sel_hi:[1,0]
	v_pk_add_f32 v[2:3], v[2:3], 0 op_sel_hi:[1,0]
	v_pk_add_f32 v[0:1], v[0:1], 0 op_sel_hi:[1,0]
	s_waitcnt vmcnt(6)
	v_pk_fma_f32 v[6:7], v[6:7], v[138:139], v[202:203]
	v_pk_fma_f32 v[4:5], v[4:5], v[136:137], v[200:201]
	v_pk_fma_f32 v[2:3], v[2:3], v[174:175], v[206:207]
	v_pk_fma_f32 v[0:1], v[0:1], v[172:173], v[204:205]
	global_store_dwordx4 v[162:163], v[4:7], off
	global_store_dwordx4 v[162:163], v[0:3], off offset:16
	s_andn2_b64 vcc, exec, s[38:39]
	s_mov_b64 s[2:3], -1
	s_cbranch_vccnz .LBB0_2563
	s_andn2_b64 vcc, exec, s[6:7]
	s_cbranch_vccnz .LBB0_2562
	s_barrier
	s_branch .LBB0_2562

; #define EPI_LOOP_ROWS _Pragma("unroll") for (int ai = 0; ai < 2; ++ai) _Pragma("unroll") for (int m = 0; m < 4; ++m)
; #define EPI_LOOP_BJ _Pragma("unroll") for (int bj = 0; bj < 2; ++bj)
;     DI void operator()(const AccT& acc, int brow, int bcol, int wr, int wc, int fr, int fq) const {
;         EPI_LOOP_BJ { const int col = bcol + bj * 128 + wc * 32 + fq * 8;
;             const f32x4 g0 = *(const f32x4*)(gate + col), g1 = *(const f32x4*)(gate + col + 4); f32x4 b0 = (f32x4){0.f, 0.f, 0.f, 0.f}, b1 = b0; if (bias) { b0 = *(const f32x4*)(bias + col); b1 = *(const f32x4*)(bias + col + 4); }
;             EPI_LOOP_ROWS { const size_t eo = (size_t)(ai * 128 + wr * 64 + m * 16 + fr) * D + col; float* q = base + eo;
;                 f32x4 x0 = (f32x4){0.f, 0.f, 0.f, 0.f}, x1 = x0; if (rmw) { x0 = *(const f32x4*)(src + eo); x1 = *(const f32x4*)(src + eo + 4); }
.LBB0_2899:
	v_lshrrev_b32_e32 v128, 1, v136
	v_and_b32_e32 v129, 0x60, v128
	v_and_b32_e32 v128, 24, v128
	v_add3_u32 v158, v129, s77, v128
	v_ashrrev_i32_e32 v159, 31, v158
	v_lshlrev_b64 v[138:139], 2, v[158:159]
	v_lshl_add_u64 v[160:161], s[4:5], 0, v[138:139]
	global_load_dwordx4 v[128:131], v[160:161], off offset:16
	global_load_dwordx4 v[132:135], v[160:161], off
	v_and_b32_e32 v137, 15, v136
	v_ashrrev_i32_e32 v136, 2, v136
	v_and_or_b32 v164, v136, s71, v137
	v_ashrrev_i32_e32 v165, 31, v164
	v_lshlrev_b64 v[136:137], 12, v[164:165]
	v_lshl_add_u64 v[162:163], s[44:45], 0, v[136:137]
	v_cndmask_b32_e64 v137, 0, 1, s[14:15]
	v_lshl_add_u64 v[166:167], v[162:163], 0, v[138:139]
	v_mov_b32_e32 v136, 0
	v_cmp_ne_u32_e64 s[4:5], 1, v137
	global_load_dwordx4 v[172:175], v[160:161], off offset:528
	global_load_dwordx4 v[136:139], v[160:161], off offset:512
	v_mov_b32_e32 v142, v166
	v_mov_b32_e32 v143, v167
	v_add_co_u32_e32 v144, vcc, 0x10000, v166
	s_nop 1
	v_addc_co_u32_e32 v145, vcc, 0, v167, vcc
	v_add_co_u32_e32 v158, vcc, 0x20000, v166
	s_nop 1
	v_addc_co_u32_e32 v159, vcc, 0, v167, vcc
	v_add_co_u32_e32 v162, vcc, 0x30000, v166
	s_nop 1
	v_addc_co_u32_e32 v163, vcc, 0, v167, vcc
	s_and_b64 vcc, exec, s[14:15]
	s_cbranch_vccz .Lrep_4_0_nold
	global_load_dwordx4 v[176:179], v[142:143], off
	global_load_dwordx4 v[180:183], v[142:143], off offset:16
	global_load_dwordx4 v[184:187], v[144:145], off
	global_load_dwordx4 v[188:191], v[144:145], off offset:16
	global_load_dwordx4 v[192:195], v[158:159], off
	global_load_dwordx4 v[196:199], v[158:159], off offset:16
	global_load_dwordx4 v[200:203], v[162:163], off
	global_load_dwordx4 v[204:207], v[162:163], off offset:16
	s_branch .Lrep_4_0_go

; #define EPI_LOOP_ROWS _Pragma("unroll") for (int ai = 0; ai < 2; ++ai) _Pragma("unroll") for (int m = 0; m < 4; ++m)
; #define EPI_LOOP_BJ _Pragma("unroll") for (int bj = 0; bj < 2; ++bj)
;     DI void operator()(const AccT& acc, int brow, int bcol, int wr, int wc, int fr, int fq) const {
;         EPI_LOOP_BJ { const int col = bcol + bj * 128 + wc * 32 + fq * 8;
;             const f32x4 g0 = *(const f32x4*)(gate + col), g1 = *(const f32x4*)(gate + col + 4); f32x4 b0 = (f32x4){0.f, 0.f, 0.f, 0.f}, b1 = b0; if (bias) { b0 = *(const f32x4*)(bias + col); b1 = *(const f32x4*)(bias + col + 4); }
;             EPI_LOOP_ROWS { const size_t eo = (size_t)(ai * 128 + wr * 64 + m * 16 + fr) * D + col; float* q = base + eo;
;                 f32x4 x0 = (f32x4){0.f, 0.f, 0.f, 0.f}, x1 = x0; if (rmw) { x0 = *(const f32x4*)(src + eo); x1 = *(const f32x4*)(src + eo + 4); }
.LBB0_3473:
	v_lshrrev_b32_e32 v128, 1, v136
	v_and_b32_e32 v129, 0x60, v128
	v_and_b32_e32 v128, 24, v128
	v_add3_u32 v158, v129, s2, v128
	v_ashrrev_i32_e32 v159, 31, v158
	v_lshlrev_b64 v[138:139], 2, v[158:159]
	v_lshl_add_u64 v[160:161], s[46:47], 0, v[138:139]
	global_load_dwordx4 v[128:131], v[160:161], off offset:16
	global_load_dwordx4 v[132:135], v[160:161], off
	v_and_b32_e32 v137, 15, v136
	v_ashrrev_i32_e32 v136, 2, v136
	v_and_or_b32 v164, v136, s58, v137
	v_ashrrev_i32_e32 v165, 31, v164
	v_lshlrev_b64 v[136:137], 12, v[164:165]
	v_lshl_add_u64 v[162:163], s[44:45], 0, v[136:137]
	v_cndmask_b32_e64 v137, 0, 1, s[14:15]
	v_lshl_add_u64 v[166:167], v[162:163], 0, v[138:139]
	v_mov_b32_e32 v136, 0
	v_cmp_ne_u32_e64 s[2:3], 1, v137
	global_load_dwordx4 v[172:175], v[160:161], off offset:528
	global_load_dwordx4 v[136:139], v[160:161], off offset:512
	v_mov_b32_e32 v142, v166
	v_mov_b32_e32 v143, v167
	v_add_co_u32_e32 v144, vcc, 0x10000, v166
	s_nop 1
	v_addc_co_u32_e32 v145, vcc, 0, v167, vcc
	v_add_co_u32_e32 v158, vcc, 0x20000, v166
	s_nop 1
	v_addc_co_u32_e32 v159, vcc, 0, v167, vcc
	v_add_co_u32_e32 v162, vcc, 0x30000, v166
	s_nop 1
	v_addc_co_u32_e32 v163, vcc, 0, v167, vcc
	s_and_b64 vcc, exec, s[14:15]
	s_cbranch_vccz .Lrep_5_0_nold
	global_load_dwordx4 v[176:179], v[142:143], off
	global_load_dwordx4 v[180:183], v[142:143], off offset:16
	global_load_dwordx4 v[184:187], v[144:145], off
	global_load_dwordx4 v[188:191], v[144:145], off offset:16
	global_load_dwordx4 v[192:195], v[158:159], off
	global_load_dwordx4 v[196:199], v[158:159], off offset:16
	global_load_dwordx4 v[200:203], v[162:163], off
	global_load_dwordx4 v[204:207], v[162:163], off offset:16
	s_branch .Lrep_5_0_go

; #define BAR __builtin_amdgcn_s_barrier()
; #define EPI_LOOP_ROWS _Pragma("unroll") for (int ai = 0; ai < 2; ++ai) _Pragma("unroll") for (int m = 0; m < 4; ++m)
; #define EPI_LOOP_BJ _Pragma("unroll") for (int bj = 0; bj < 2; ++bj)
; template <class Get, class Epi>
; DI void gemm_loop(int ntiles, int ld, char* shm, const Get& get, const Epi& epi) {
;     ...
;         if (!has_next) break;
;         G_ZERO;
;         cur = nxt; cA = nA; cB = nB; L = Ln;
;         if (wr == 1) BAR;
;     DI void operator()(const AccT& acc, int brow, int bcol, int wr, int wc, int fr, int fq) const {
;         EPI_LOOP_BJ { const int col = bcol + bj * 128 + wc * 32 + fq * 8;
;             const f32x4 g0 = *(const f32x4*)(gate + col), g1 = *(const f32x4*)(gate + col + 4); f32x4 b0 = (f32x4){0.f, 0.f, 0.f, 0.f}, b1 = b0; if (bias) { b0 = *(const f32x4*)(bias + col); b1 = *(const f32x4*)(bias + col + 4); }
;             EPI_LOOP_ROWS { const size_t eo = (size_t)(ai * 128 + wr * 64 + m * 16 + fr) * D + col; float* q = base + eo;
;                 f32x4 x0 = (f32x4){0.f, 0.f, 0.f, 0.f}, x1 = x0; if (rmw) { x0 = *(const f32x4*)(src + eo); x1 = *(const f32x4*)(src + eo + 4); }
;                 x0 += g0 * (acc[ai][bj][m][0] + b0); x1 += g1 * (acc[ai][bj][m][1] + b1); *(f32x4*)q = x0; *(f32x4*)(q + 4) = x1; } }
.Lrep_5_3_go:
	v_pk_add_f32 v[30:31], v[30:31], 0 op_sel_hi:[1,0]
	v_pk_add_f32 v[28:29], v[28:29], 0 op_sel_hi:[1,0]
	v_pk_add_f32 v[26:27], v[26:27], 0 op_sel_hi:[1,0]
	v_pk_add_f32 v[24:25], v[24:25], 0 op_sel_hi:[1,0]
	s_waitcnt vmcnt(6)
	v_pk_fma_f32 v[30:31], v[30:31], v[138:139], v[178:179]
	v_pk_fma_f32 v[28:29], v[28:29], v[136:137], v[176:177]
	v_pk_fma_f32 v[26:27], v[26:27], v[174:175], v[182:183]
	v_pk_fma_f32 v[24:25], v[24:25], v[172:173], v[180:181]
	global_store_dwordx4 v[142:143], v[28:31], off
	global_store_dwordx4 v[142:143], v[24:27], off offset:16
	v_pk_add_f32 v[22:23], v[22:23], 0 op_sel_hi:[1,0]
	v_pk_add_f32 v[20:21], v[20:21], 0 op_sel_hi:[1,0]
	v_pk_add_f32 v[18:19], v[18:19], 0 op_sel_hi:[1,0]
	v_pk_add_f32 v[16:17], v[16:17], 0 op_sel_hi:[1,0]
	s_waitcnt vmcnt(6)
	v_pk_fma_f32 v[22:23], v[22:23], v[138:139], v[186:187]
	v_pk_fma_f32 v[20:21], v[20:21], v[136:137], v[184:185]
	v_pk_fma_f32 v[18:19], v[18:19], v[174:175], v[190:191]
	v_pk_fma_f32 v[16:17], v[16:17], v[172:173], v[188:189]
	global_store_dwordx4 v[144:145], v[20:23], off
	global_store_dwordx4 v[144:145], v[16:19], off offset:16
	v_pk_add_f32 v[14:15], v[14:15], 0 op_sel_hi:[1,0]
	v_pk_add_f32 v[12:13], v[12:13], 0 op_sel_hi:[1,0]
	v_pk_add_f32 v[8:9], v[8:9], 0 op_sel_hi:[1,0]
	v_pk_add_f32 v[10:11], v[10:11], 0 op_sel_hi:[1,0]
	s_waitcnt vmcnt(6)
	v_pk_fma_f32 v[14:15], v[14:15], v[138:139], v[194:195]
	v_pk_fma_f32 v[12:13], v[12:13], v[136:137], v[192:193]
	v_pk_fma_f32 v[8:9], v[8:9], v[172:173], v[196:197]
	v_pk_fma_f32 v[10:11], v[10:11], v[174:175], v[198:199]
	global_store_dwordx4 v[158:159], v[12:15], off
	global_store_dwordx4 v[158:159], v[8:11], off offset:16
	v_pk_add_f32 v[6:7], v[6:7], 0 op_sel_hi:[1,0]
	v_pk_add_f32 v[4:5], v[4:5], 0 op_sel_hi:[1,0]
	v_pk_add_f32 v[2:3], v[2:3], 0 op_sel_hi:[1,0]
	v_pk_add_f32 v[0:1], v[0:1], 0 op_sel_hi:[1,0]
	s_waitcnt vmcnt(6)
	v_pk_fma_f32 v[6:7], v[6:7], v[138:139], v[202:203]
	v_pk_fma_f32 v[4:5], v[4:5], v[136:137], v[200:201]
	v_pk_fma_f32 v[2:3], v[2:3], v[174:175], v[206:207]
	v_pk_fma_f32 v[0:1], v[0:1], v[172:173], v[204:205]
	global_store_dwordx4 v[162:163], v[4:7], off
	global_store_dwordx4 v[162:163], v[0:3], off offset:16
	s_andn2_b64 vcc, exec, s[30:31]
	s_mov_b64 s[2:3], -1
	s_cbranch_vccnz .LBB0_3458
	s_andn2_b64 vcc, exec, s[0:1]
	s_cbranch_vccnz .LBB0_3457
	s_barrier
	s_branch .LBB0_3457

; #define EPI_LOOP_ROWS _Pragma("unroll") for (int ai = 0; ai < 2; ++ai) _Pragma("unroll") for (int m = 0; m < 4; ++m)
; #define EPI_LOOP_BJ _Pragma("unroll") for (int bj = 0; bj < 2; ++bj)
;     DI void operator()(const AccT& acc, int brow, int bcol, int wr, int wc, int fr, int fq) const {
;         EPI_LOOP_BJ { const int col = bcol + bj * 128 + wc * 32 + fq * 8;
;             const f32x4 g0 = *(const f32x4*)(gate + col), g1 = *(const f32x4*)(gate + col + 4); f32x4 b0 = (f32x4){0.f, 0.f, 0.f, 0.f}, b1 = b0; if (bias) { b0 = *(const f32x4*)(bias + col); b1 = *(const f32x4*)(bias + col + 4); }
;             EPI_LOOP_ROWS { const size_t eo = (size_t)(ai * 128 + wr * 64 + m * 16 + fr) * D + col; float* q = base + eo;
;                 f32x4 x0 = (f32x4){0.f, 0.f, 0.f, 0.f}, x1 = x0; if (rmw) { x0 = *(const f32x4*)(src + eo); x1 = *(const f32x4*)(src + eo + 4); }
.LBB0_3766:
	v_lshrrev_b32_e32 v128, 1, v136
	v_and_b32_e32 v129, 0x60, v128
	v_and_b32_e32 v128, 24, v128
	v_add3_u32 v158, v129, s51, v128
	v_ashrrev_i32_e32 v159, 31, v158
	v_lshlrev_b64 v[138:139], 2, v[158:159]
	v_lshl_add_u64 v[160:161], s[2:3], 0, v[138:139]
	global_load_dwordx4 v[128:131], v[160:161], off offset:16
	global_load_dwordx4 v[132:135], v[160:161], off
	v_and_b32_e32 v137, 15, v136
	v_ashrrev_i32_e32 v136, 2, v136
	v_and_or_b32 v164, v136, s46, v137
	v_ashrrev_i32_e32 v165, 31, v164
	v_lshlrev_b64 v[136:137], 12, v[164:165]
	v_lshl_add_u64 v[162:163], s[24:25], 0, v[136:137]
	v_cndmask_b32_e64 v137, 0, 1, s[30:31]
	v_lshl_add_u64 v[166:167], v[162:163], 0, v[138:139]
	v_mov_b32_e32 v136, 0
	v_cmp_ne_u32_e64 s[2:3], 1, v137
	global_load_dwordx4 v[172:175], v[160:161], off offset:528
	global_load_dwordx4 v[136:139], v[160:161], off offset:512
	v_mov_b32_e32 v142, v166
	v_mov_b32_e32 v143, v167
	v_add_co_u32_e32 v144, vcc, 0x10000, v166
	s_nop 1
	v_addc_co_u32_e32 v145, vcc, 0, v167, vcc
	v_add_co_u32_e32 v158, vcc, 0x20000, v166
	s_nop 1
	v_addc_co_u32_e32 v159, vcc, 0, v167, vcc
	v_add_co_u32_e32 v162, vcc, 0x30000, v166
	s_nop 1
	v_addc_co_u32_e32 v163, vcc, 0, v167, vcc
	s_and_b64 vcc, exec, s[30:31]
	s_cbranch_vccz .Lrep_6_0_nold
	global_load_dwordx4 v[176:179], v[142:143], off
	global_load_dwordx4 v[180:183], v[142:143], off offset:16
	global_load_dwordx4 v[184:187], v[144:145], off
	global_load_dwordx4 v[188:191], v[144:145], off offset:16
	global_load_dwordx4 v[192:195], v[158:159], off
	global_load_dwordx4 v[196:199], v[158:159], off offset:16
	global_load_dwordx4 v[200:203], v[162:163], off
	global_load_dwordx4 v[204:207], v[162:163], off offset:16
	s_branch .Lrep_6_0_go

; #define EPI_LOOP_ROWS _Pragma("unroll") for (int ai = 0; ai < 2; ++ai) _Pragma("unroll") for (int m = 0; m < 4; ++m)
; #define EPI_LOOP_BJ _Pragma("unroll") for (int bj = 0; bj < 2; ++bj)
;     DI void operator()(const AccT& acc, int brow, int bcol, int wr, int wc, int fr, int fq) const {
;         EPI_LOOP_BJ { const int col = bcol + bj * 128 + wc * 32 + fq * 8;
;             const f32x4 g0 = *(const f32x4*)(gate + col), g1 = *(const f32x4*)(gate + col + 4); f32x4 b0 = (f32x4){0.f, 0.f, 0.f, 0.f}, b1 = b0; if (bias) { b0 = *(const f32x4*)(bias + col); b1 = *(const f32x4*)(bias + col + 4); }
;             EPI_LOOP_ROWS { const size_t eo = (size_t)(ai * 128 + wr * 64 + m * 16 + fr) * D + col; float* q = base + eo;
;                 f32x4 x0 = (f32x4){0.f, 0.f, 0.f, 0.f}, x1 = x0; if (rmw) { x0 = *(const f32x4*)(src + eo); x1 = *(const f32x4*)(src + eo + 4); }
;                 x0 += g0 * (acc[ai][bj][m][0] + b0); x1 += g1 * (acc[ai][bj][m][1] + b1); *(f32x4*)q = x0; *(f32x4*)(q + 4) = x1; } }
.Lrep_6_0_go:
	v_pk_add_f32 v[126:127], v[126:127], 0 op_sel_hi:[1,0]
	v_pk_add_f32 v[124:125], v[124:125], 0 op_sel_hi:[1,0]
	v_pk_add_f32 v[120:121], v[120:121], 0 op_sel_hi:[1,0]
	v_pk_add_f32 v[122:123], v[122:123], 0 op_sel_hi:[1,0]
	s_waitcnt vmcnt(6)
	v_pk_fma_f32 v[126:127], v[126:127], v[134:135], v[178:179]
	v_pk_fma_f32 v[124:125], v[124:125], v[132:133], v[176:177]
	v_pk_fma_f32 v[120:121], v[120:121], v[128:129], v[180:181]
	v_pk_fma_f32 v[122:123], v[122:123], v[130:131], v[182:183]
	global_store_dwordx4 v[142:143], v[124:127], off
	global_store_dwordx4 v[142:143], v[120:123], off offset:16
	v_pk_add_f32 v[118:119], v[118:119], 0 op_sel_hi:[1,0]
	v_pk_add_f32 v[116:117], v[116:117], 0 op_sel_hi:[1,0]
	v_pk_add_f32 v[112:113], v[112:113], 0 op_sel_hi:[1,0]
	v_pk_add_f32 v[114:115], v[114:115], 0 op_sel_hi:[1,0]
	s_waitcnt vmcnt(6)
	v_pk_fma_f32 v[118:119], v[118:119], v[134:135], v[186:187]
	v_pk_fma_f32 v[116:117], v[116:117], v[132:133], v[184:185]
	v_pk_fma_f32 v[112:113], v[112:113], v[128:129], v[188:189]
	v_pk_fma_f32 v[114:115], v[114:115], v[130:131], v[190:191]
	global_store_dwordx4 v[144:145], v[116:119], off
	global_store_dwordx4 v[144:145], v[112:115], off offset:16
	v_pk_add_f32 v[110:111], v[110:111], 0 op_sel_hi:[1,0]
	v_pk_add_f32 v[108:109], v[108:109], 0 op_sel_hi:[1,0]
	v_pk_add_f32 v[104:105], v[104:105], 0 op_sel_hi:[1,0]
	v_pk_add_f32 v[106:107], v[106:107], 0 op_sel_hi:[1,0]
	s_waitcnt vmcnt(6)
	v_pk_fma_f32 v[110:111], v[110:111], v[134:135], v[194:195]
	v_pk_fma_f32 v[108:109], v[108:109], v[132:133], v[192:193]
	v_pk_fma_f32 v[104:105], v[104:105], v[128:129], v[196:197]
	v_pk_fma_f32 v[106:107], v[106:107], v[130:131], v[198:199]
	global_store_dwordx4 v[158:159], v[108:111], off
	global_store_dwordx4 v[158:159], v[104:107], off offset:16
	v_pk_add_f32 v[102:103], v[102:103], 0 op_sel_hi:[1,0]
	v_pk_add_f32 v[100:101], v[100:101], 0 op_sel_hi:[1,0]
	v_pk_add_f32 v[96:97], v[96:97], 0 op_sel_hi:[1,0]
	v_pk_add_f32 v[98:99], v[98:99], 0 op_sel_hi:[1,0]
	s_waitcnt vmcnt(6)
	v_pk_fma_f32 v[102:103], v[102:103], v[134:135], v[202:203]
	v_pk_fma_f32 v[100:101], v[100:101], v[132:133], v[200:201]
	v_pk_fma_f32 v[96:97], v[96:97], v[128:129], v[204:205]
	v_pk_fma_f32 v[98:99], v[98:99], v[130:131], v[206:207]
	global_store_dwordx4 v[162:163], v[100:103], off
	global_store_dwordx4 v[162:163], v[96:99], off offset:16
	v_add_co_u32_e32 v142, vcc, 0x80000, v166
	s_nop 1
	v_addc_co_u32_e32 v143, vcc, 0, v167, vcc
	v_add_co_u32_e32 v144, vcc, 0x90000, v166
	s_nop 1
	v_addc_co_u32_e32 v145, vcc, 0, v167, vcc
	v_add_co_u32_e32 v158, vcc, 0xa0000, v166
	s_nop 1
	v_addc_co_u32_e32 v159, vcc, 0, v167, vcc
	v_add_co_u32_e32 v162, vcc, 0xb0000, v166
	s_nop 1
	v_addc_co_u32_e32 v163, vcc, 0, v167, vcc
	s_and_b64 vcc, exec, s[30:31]
	s_cbranch_vccz .Lrep_6_1_nold
	global_load_dwordx4 v[176:179], v[142:143], off
	global_load_dwordx4 v[180:183], v[142:143], off offset:16
	global_load_dwordx4 v[184:187], v[144:145], off
	global_load_dwordx4 v[188:191], v[144:145], off offset:16
	global_load_dwordx4 v[192:195], v[158:159], off
	global_load_dwordx4 v[196:199], v[158:159], off offset:16
	global_load_dwordx4 v[200:203], v[162:163], off
	global_load_dwordx4 v[204:207], v[162:163], off offset:16
	s_branch .Lrep_6_1_go

; #define EPI_LOOP_ROWS _Pragma("unroll") for (int ai = 0; ai < 2; ++ai) _Pragma("unroll") for (int m = 0; m < 4; ++m)
; #define EPI_LOOP_BJ _Pragma("unroll") for (int bj = 0; bj < 2; ++bj)
;     DI void operator()(const AccT& acc, int brow, int bcol, int wr, int wc, int fr, int fq) const {
;         EPI_LOOP_BJ { const int col = bcol + bj * 128 + wc * 32 + fq * 8;
;             const f32x4 g0 = *(const f32x4*)(gate + col), g1 = *(const f32x4*)(gate + col + 4); f32x4 b0 = (f32x4){0.f, 0.f, 0.f, 0.f}, b1 = b0; if (bias) { b0 = *(const f32x4*)(bias + col); b1 = *(const f32x4*)(bias + col + 4); }
;             EPI_LOOP_ROWS { const size_t eo = (size_t)(ai * 128 + wr * 64 + m * 16 + fr) * D + col; float* q = base + eo;
;                 f32x4 x0 = (f32x4){0.f, 0.f, 0.f, 0.f}, x1 = x0; if (rmw) { x0 = *(const f32x4*)(src + eo); x1 = *(const f32x4*)(src + eo + 4); }
;                 x0 += g0 * (acc[ai][bj][m][0] + b0); x1 += g1 * (acc[ai][bj][m][1] + b1); *(f32x4*)q = x0; *(f32x4*)(q + 4) = x1; } }
.Lrep_6_1_go:
	v_pk_add_f32 v[94:95], v[94:95], 0 op_sel_hi:[1,0]
	v_pk_add_f32 v[92:93], v[92:93], 0 op_sel_hi:[1,0]
	v_pk_add_f32 v[90:91], v[90:91], 0 op_sel_hi:[1,0]
	v_pk_add_f32 v[88:89], v[88:89], 0 op_sel_hi:[1,0]
	s_waitcnt vmcnt(6)
	v_pk_fma_f32 v[94:95], v[94:95], v[134:135], v[178:179]
	v_pk_fma_f32 v[92:93], v[92:93], v[132:133], v[176:177]
	v_pk_fma_f32 v[90:91], v[90:91], v[130:131], v[182:183]
	v_pk_fma_f32 v[88:89], v[88:89], v[128:129], v[180:181]
	global_store_dwordx4 v[142:143], v[92:95], off
	global_store_dwordx4 v[142:143], v[88:91], off offset:16
	v_pk_add_f32 v[86:87], v[86:87], 0 op_sel_hi:[1,0]
	v_pk_add_f32 v[84:85], v[84:85], 0 op_sel_hi:[1,0]
	v_pk_add_f32 v[80:81], v[80:81], 0 op_sel_hi:[1,0]
	v_pk_add_f32 v[82:83], v[82:83], 0 op_sel_hi:[1,0]
	s_waitcnt vmcnt(6)
	v_pk_fma_f32 v[86:87], v[86:87], v[134:135], v[186:187]
	v_pk_fma_f32 v[84:85], v[84:85], v[132:133], v[184:185]
	v_pk_fma_f32 v[80:81], v[80:81], v[128:129], v[188:189]
	v_pk_fma_f32 v[82:83], v[82:83], v[130:131], v[190:191]
	global_store_dwordx4 v[144:145], v[84:87], off
	global_store_dwordx4 v[144:145], v[80:83], off offset:16
	v_pk_add_f32 v[74:75], v[74:75], 0 op_sel_hi:[1,0]
	v_pk_add_f32 v[78:79], v[78:79], 0 op_sel_hi:[1,0]
	v_pk_add_f32 v[76:77], v[76:77], 0 op_sel_hi:[1,0]
	v_pk_add_f32 v[72:73], v[72:73], 0 op_sel_hi:[1,0]
	s_waitcnt vmcnt(6)
	v_pk_fma_f32 v[74:75], v[74:75], v[130:131], v[198:199]
	v_pk_fma_f32 v[78:79], v[78:79], v[134:135], v[194:195]
	v_pk_fma_f32 v[76:77], v[76:77], v[132:133], v[192:193]
	v_pk_fma_f32 v[72:73], v[72:73], v[128:129], v[196:197]
	global_store_dwordx4 v[158:159], v[76:79], off
	global_store_dwordx4 v[158:159], v[72:75], off offset:16
	v_pk_add_f32 v[70:71], v[70:71], 0 op_sel_hi:[1,0]
	v_pk_add_f32 v[68:69], v[68:69], 0 op_sel_hi:[1,0]
	v_pk_add_f32 v[66:67], v[66:67], 0 op_sel_hi:[1,0]
	v_pk_add_f32 v[64:65], v[64:65], 0 op_sel_hi:[1,0]
	s_waitcnt vmcnt(6)
	v_pk_fma_f32 v[70:71], v[70:71], v[134:135], v[202:203]
	v_pk_fma_f32 v[68:69], v[68:69], v[132:133], v[200:201]
	v_pk_fma_f32 v[66:67], v[66:67], v[130:131], v[206:207]
	v_pk_fma_f32 v[64:65], v[64:65], v[128:129], v[204:205]
	global_store_dwordx4 v[162:163], v[68:71], off
	global_store_dwordx4 v[162:163], v[64:67], off offset:16
	v_add_co_u32_e32 v142, vcc, 0x200, v166
	s_nop 1
	v_addc_co_u32_e32 v143, vcc, 0, v167, vcc
	v_add_co_u32_e32 v144, vcc, 0x10200, v166
	s_nop 1
	v_addc_co_u32_e32 v145, vcc, 0, v167, vcc
	v_add_co_u32_e32 v158, vcc, 0x20200, v166
	s_nop 1
	v_addc_co_u32_e32 v159, vcc, 0, v167, vcc
	v_add_co_u32_e32 v162, vcc, 0x30200, v166
	s_nop 1
	v_addc_co_u32_e32 v163, vcc, 0, v167, vcc
	s_and_b64 vcc, exec, s[30:31]
	s_cbranch_vccz .Lrep_6_2_nold
	global_load_dwordx4 v[176:179], v[142:143], off
	global_load_dwordx4 v[180:183], v[142:143], off offset:16
	global_load_dwordx4 v[184:187], v[144:145], off
	global_load_dwordx4 v[188:191], v[144:145], off offset:16
	global_load_dwordx4 v[192:195], v[158:159], off
	global_load_dwordx4 v[196:199], v[158:159], off offset:16
	global_load_dwordx4 v[200:203], v[162:163], off
	global_load_dwordx4 v[204:207], v[162:163], off offset:16
	s_branch .Lrep_6_2_go

; #define EPI_LOOP_ROWS _Pragma("unroll") for (int ai = 0; ai < 2; ++ai) _Pragma("unroll") for (int m = 0; m < 4; ++m)
; #define EPI_LOOP_BJ _Pragma("unroll") for (int bj = 0; bj < 2; ++bj)
;     DI void operator()(const AccT& acc, int brow, int bcol, int wr, int wc, int fr, int fq) const {
;         EPI_LOOP_BJ { const int col = bcol + bj * 128 + wc * 32 + fq * 8;
;             const f32x4 g0 = *(const f32x4*)(gate + col), g1 = *(const f32x4*)(gate + col + 4); f32x4 b0 = (f32x4){0.f, 0.f, 0.f, 0.f}, b1 = b0; if (bias) { b0 = *(const f32x4*)(bias + col); b1 = *(const f32x4*)(bias + col + 4); }
;             EPI_LOOP_ROWS { const size_t eo = (size_t)(ai * 128 + wr * 64 + m * 16 + fr) * D + col; float* q = base + eo;
;                 f32x4 x0 = (f32x4){0.f, 0.f, 0.f, 0.f}, x1 = x0; if (rmw) { x0 = *(const f32x4*)(src + eo); x1 = *(const f32x4*)(src + eo + 4); }
;                 x0 += g0 * (acc[ai][bj][m][0] + b0); x1 += g1 * (acc[ai][bj][m][1] + b1); *(f32x4*)q = x0; *(f32x4*)(q + 4) = x1; } }
.Lrep_6_2_go:
	v_pk_add_f32 v[62:63], v[62:63], 0 op_sel_hi:[1,0]
	v_pk_add_f32 v[60:61], v[60:61], 0 op_sel_hi:[1,0]
	v_pk_add_f32 v[58:59], v[58:59], 0 op_sel_hi:[1,0]
	v_pk_add_f32 v[56:57], v[56:57], 0 op_sel_hi:[1,0]
	s_waitcnt vmcnt(6)
	v_pk_fma_f32 v[62:63], v[62:63], v[138:139], v[178:179]
	v_pk_fma_f32 v[60:61], v[60:61], v[136:137], v[176:177]
	v_pk_fma_f32 v[58:59], v[58:59], v[174:175], v[182:183]
	v_pk_fma_f32 v[56:57], v[56:57], v[172:173], v[180:181]
	global_store_dwordx4 v[142:143], v[60:63], off
	global_store_dwordx4 v[142:143], v[56:59], off offset:16
	v_pk_add_f32 v[54:55], v[54:55], 0 op_sel_hi:[1,0]
	v_pk_add_f32 v[52:53], v[52:53], 0 op_sel_hi:[1,0]
	v_pk_add_f32 v[50:51], v[50:51], 0 op_sel_hi:[1,0]
	v_pk_add_f32 v[48:49], v[48:49], 0 op_sel_hi:[1,0]
	s_waitcnt vmcnt(6)
	v_pk_fma_f32 v[54:55], v[54:55], v[138:139], v[186:187]
	v_pk_fma_f32 v[52:53], v[52:53], v[136:137], v[184:185]
	v_pk_fma_f32 v[50:51], v[50:51], v[174:175], v[190:191]
	v_pk_fma_f32 v[48:49], v[48:49], v[172:173], v[188:189]
	global_store_dwordx4 v[144:145], v[52:55], off
	global_store_dwordx4 v[144:145], v[48:51], off offset:16
	v_pk_add_f32 v[46:47], v[46:47], 0 op_sel_hi:[1,0]
	v_pk_add_f32 v[44:45], v[44:45], 0 op_sel_hi:[1,0]
	v_pk_add_f32 v[42:43], v[42:43], 0 op_sel_hi:[1,0]
	v_pk_add_f32 v[40:41], v[40:41], 0 op_sel_hi:[1,0]
	s_waitcnt vmcnt(6)
	v_pk_fma_f32 v[46:47], v[46:47], v[138:139], v[194:195]
	v_pk_fma_f32 v[44:45], v[44:45], v[136:137], v[192:193]
	v_pk_fma_f32 v[42:43], v[42:43], v[174:175], v[198:199]
	v_pk_fma_f32 v[40:41], v[40:41], v[172:173], v[196:197]
	global_store_dwordx4 v[158:159], v[44:47], off
	global_store_dwordx4 v[158:159], v[40:43], off offset:16
	v_pk_add_f32 v[38:39], v[38:39], 0 op_sel_hi:[1,0]
	v_pk_add_f32 v[36:37], v[36:37], 0 op_sel_hi:[1,0]
	v_pk_add_f32 v[34:35], v[34:35], 0 op_sel_hi:[1,0]
	v_pk_add_f32 v[32:33], v[32:33], 0 op_sel_hi:[1,0]
	s_waitcnt vmcnt(6)
	v_pk_fma_f32 v[38:39], v[38:39], v[138:139], v[202:203]
	v_pk_fma_f32 v[36:37], v[36:37], v[136:137], v[200:201]
	v_pk_fma_f32 v[34:35], v[34:35], v[174:175], v[206:207]
	v_pk_fma_f32 v[32:33], v[32:33], v[172:173], v[204:205]
	global_store_dwordx4 v[162:163], v[36:39], off
	global_store_dwordx4 v[162:163], v[32:35], off offset:16
	v_add_co_u32_e32 v142, vcc, 0x80200, v166
	s_nop 1
	v_addc_co_u32_e32 v143, vcc, 0, v167, vcc
	v_add_co_u32_e32 v144, vcc, 0x90200, v166
	s_nop 1
	v_addc_co_u32_e32 v145, vcc, 0, v167, vcc
	v_add_co_u32_e32 v158, vcc, 0xa0200, v166
	s_nop 1
	v_addc_co_u32_e32 v159, vcc, 0, v167, vcc
	v_add_co_u32_e32 v162, vcc, 0xb0200, v166
	s_nop 1
	v_addc_co_u32_e32 v163, vcc, 0, v167, vcc
	s_and_b64 vcc, exec, s[30:31]
	s_cbranch_vccz .Lrep_6_3_nold
	global_load_dwordx4 v[176:179], v[142:143], off
	global_load_dwordx4 v[180:183], v[142:143], off offset:16
	global_load_dwordx4 v[184:187], v[144:145], off
	global_load_dwordx4 v[188:191], v[144:145], off offset:16
	global_load_dwordx4 v[192:195], v[158:159], off
	global_load_dwordx4 v[196:199], v[158:159], off offset:16
	global_load_dwordx4 v[200:203], v[162:163], off
	global_load_dwordx4 v[204:207], v[162:163], off offset:16
	s_branch .Lrep_6_3_go

; #define BAR __builtin_amdgcn_s_barrier()
; #define EPI_LOOP_ROWS _Pragma("unroll") for (int ai = 0; ai < 2; ++ai) _Pragma("unroll") for (int m = 0; m < 4; ++m)
; #define EPI_LOOP_BJ _Pragma("unroll") for (int bj = 0; bj < 2; ++bj)
; template <class Get, class Epi>
; DI void gemm_loop(int ntiles, int ld, char* shm, const Get& get, const Epi& epi) {
;     ...
;         if (!has_next) break;
;         G_ZERO;
;         cur = nxt; cA = nA; cB = nB; L = Ln;
;         if (wr == 1) BAR;
;     DI void operator()(const AccT& acc, int brow, int bcol, int wr, int wc, int fr, int fq) const {
;         EPI_LOOP_BJ { const int col = bcol + bj * 128 + wc * 32 + fq * 8;
;             const f32x4 g0 = *(const f32x4*)(gate + col), g1 = *(const f32x4*)(gate + col + 4); f32x4 b0 = (f32x4){0.f, 0.f, 0.f, 0.f}, b1 = b0; if (bias) { b0 = *(const f32x4*)(bias + col); b1 = *(const f32x4*)(bias + col + 4); }
;             EPI_LOOP_ROWS { const size_t eo = (size_t)(ai * 128 + wr * 64 + m * 16 + fr) * D + col; float* q = base + eo;
;                 f32x4 x0 = (f32x4){0.f, 0.f, 0.f, 0.f}, x1 = x0; if (rmw) { x0 = *(const f32x4*)(src + eo); x1 = *(const f32x4*)(src + eo + 4); }
;                 x0 += g0 * (acc[ai][bj][m][0] + b0); x1 += g1 * (acc[ai][bj][m][1] + b1); *(f32x4*)q = x0; *(f32x4*)(q + 4) = x1; } }
.Lrep_6_3_go:
	v_pk_add_f32 v[30:31], v[30:31], 0 op_sel_hi:[1,0]
	v_pk_add_f32 v[28:29], v[28:29], 0 op_sel_hi:[1,0]
	v_pk_add_f32 v[26:27], v[26:27], 0 op_sel_hi:[1,0]
	v_pk_add_f32 v[24:25], v[24:25], 0 op_sel_hi:[1,0]
	s_waitcnt vmcnt(6)
	v_pk_fma_f32 v[30:31], v[30:31], v[138:139], v[178:179]
	v_pk_fma_f32 v[28:29], v[28:29], v[136:137], v[176:177]
	v_pk_fma_f32 v[26:27], v[26:27], v[174:175], v[182:183]
	v_pk_fma_f32 v[24:25], v[24:25], v[172:173], v[180:181]
	global_store_dwordx4 v[142:143], v[28:31], off
	global_store_dwordx4 v[142:143], v[24:27], off offset:16
	v_pk_add_f32 v[22:23], v[22:23], 0 op_sel_hi:[1,0]
	v_pk_add_f32 v[20:21], v[20:21], 0 op_sel_hi:[1,0]
	v_pk_add_f32 v[18:19], v[18:19], 0 op_sel_hi:[1,0]
	v_pk_add_f32 v[16:17], v[16:17], 0 op_sel_hi:[1,0]
	s_waitcnt vmcnt(6)
	v_pk_fma_f32 v[22:23], v[22:23], v[138:139], v[186:187]
	v_pk_fma_f32 v[20:21], v[20:21], v[136:137], v[184:185]
	v_pk_fma_f32 v[18:19], v[18:19], v[174:175], v[190:191]
	v_pk_fma_f32 v[16:17], v[16:17], v[172:173], v[188:189]
	global_store_dwordx4 v[144:145], v[20:23], off
	global_store_dwordx4 v[144:145], v[16:19], off offset:16
	v_pk_add_f32 v[14:15], v[14:15], 0 op_sel_hi:[1,0]
	v_pk_add_f32 v[12:13], v[12:13], 0 op_sel_hi:[1,0]
	v_pk_add_f32 v[8:9], v[8:9], 0 op_sel_hi:[1,0]
	v_pk_add_f32 v[10:11], v[10:11], 0 op_sel_hi:[1,0]
	s_waitcnt vmcnt(6)
	v_pk_fma_f32 v[14:15], v[14:15], v[138:139], v[194:195]
	v_pk_fma_f32 v[12:13], v[12:13], v[136:137], v[192:193]
	v_pk_fma_f32 v[8:9], v[8:9], v[172:173], v[196:197]
	v_pk_fma_f32 v[10:11], v[10:11], v[174:175], v[198:199]
	global_store_dwordx4 v[158:159], v[12:15], off
	global_store_dwordx4 v[158:159], v[8:11], off offset:16
	v_pk_add_f32 v[6:7], v[6:7], 0 op_sel_hi:[1,0]
	v_pk_add_f32 v[4:5], v[4:5], 0 op_sel_hi:[1,0]
	v_pk_add_f32 v[2:3], v[2:3], 0 op_sel_hi:[1,0]
	v_pk_add_f32 v[0:1], v[0:1], 0 op_sel_hi:[1,0]
	s_waitcnt vmcnt(6)
	v_pk_fma_f32 v[6:7], v[6:7], v[138:139], v[202:203]
	v_pk_fma_f32 v[4:5], v[4:5], v[136:137], v[200:201]
	v_pk_fma_f32 v[2:3], v[2:3], v[174:175], v[206:207]
	v_pk_fma_f32 v[0:1], v[0:1], v[172:173], v[204:205]
	global_store_dwordx4 v[162:163], v[4:7], off
	global_store_dwordx4 v[162:163], v[0:3], off offset:16
	s_and_b64 vcc, exec, s[0:1]
	s_mov_b64 s[0:1], -1
	s_cbranch_vccnz .LBB0_3747
	s_andn2_b64 vcc, exec, s[4:5]
	s_cbranch_vccnz .LBB0_3746
	s_barrier
	s_branch .LBB0_3746
